# E22 + final RMSNorm rows software-pipelined (prefetch next row into a second register set)
# baseline (speedup 1.0000x reference)
; __global__ void __launch_bounds__(NWAVES * 64, 2) mk_fwd(Args args) {
;     ...
;         for (int m = gw; m < SEQ; m += NGW) {
;             const f32x4* xr = (const f32x4*)(XR + (size_t)m * DMODEL) + lane;
;             f32x4 v[8]; float s = 0.f;
; #pragma unroll
;             for (int j = 0; j < 8; ++j) { v[j] = xr[64 * j]; s += (v[j][0] * v[j][0] + v[j][1] * v[j][1]) + (v[j][2] * v[j][2] + v[j][3] * v[j][3]); }
;             const float rstd = __builtin_amdgcn_rsqf(wave_sum(s) * (1.f / DMODEL) + EPS);
;             f32x4* o = (f32x4*)(out_p + (size_t)m * DMODEL) + lane;
; #pragma unroll
;             for (int j = 0; j < 8; ++j) { const f32x4 g = *((const f32x4*)final_norm_w + lane + 64 * j); o[64 * j] = v[j] * rstd * g; }
.LBB0_883:
	s_ashr_i32 s0, s0, 6
	s_lshl_b32 s1, s81, 3
	s_add_i32 s4, s1, s0
	s_mov_b64 s[6:7], 0
	s_cmpk_gt_i32 s4, 0x3fff
	s_cbranch_scc1 .LBB0_886
	v_and_b32_e32 v1, 64, v252
	v_add_u32_e32 v1, 64, v1
	v_xor_b32_e32 v2, 1, v252
	v_cmp_lt_i32_e32 vcc, v2, v1
	s_add_u32 s8, s62, s6
	s_addc_u32 s9, s63, s7
	v_cndmask_b32_e32 v2, v252, v2, vcc
	v_lshlrev_b32_e32 v12, 2, v2
	v_xor_b32_e32 v2, 2, v252
	v_cmp_lt_i32_e32 vcc, v2, v1
	s_load_dwordx4 s[0:3], s[8:9], 0x60
	v_and_b32_e32 v0, 63, v0
	v_cndmask_b32_e32 v2, v252, v2, vcc
	v_lshlrev_b32_e32 v13, 2, v2
	v_xor_b32_e32 v2, 4, v252
	v_cmp_lt_i32_e32 vcc, v2, v1
	v_lshlrev_b32_e32 v0, 4, v0
	s_ashr_i32 s5, s4, 31
	v_cndmask_b32_e32 v2, v252, v2, vcc
	v_lshlrev_b32_e32 v14, 2, v2
	v_xor_b32_e32 v2, 8, v252
	v_cmp_lt_i32_e32 vcc, v2, v1
	v_mov_b32_e32 v18, 0x358637bd
	s_movk_i32 s8, 0x1000
	v_cndmask_b32_e32 v2, v252, v2, vcc
	v_lshlrev_b32_e32 v15, 2, v2
	v_xor_b32_e32 v2, 16, v252
	v_cmp_lt_i32_e32 vcc, v2, v1
	s_nop 1
	v_cndmask_b32_e32 v2, v252, v2, vcc
	v_lshlrev_b32_e32 v16, 2, v2
	v_xor_b32_e32 v2, 32, v252
	v_cmp_lt_i32_e32 vcc, v2, v1
	s_nop 1
	v_cndmask_b32_e32 v1, v252, v2, vcc
	v_lshlrev_b32_e32 v17, 2, v1
	v_mov_b32_e32 v1, 0
	s_waitcnt lgkmcnt(0)
	v_lshl_add_u64 v[2:3], s[0:1], 0, v[0:1]
	s_mov_b64 s[0:1], 0x1000
	v_lshl_add_u64 v[4:5], v[2:3], 0, s[0:1]
	s_mov_b64 s[0:1], 0x1400
	v_lshl_add_u64 v[6:7], v[2:3], 0, s[0:1]
	s_mov_b64 s[0:1], 0x1800
	v_lshl_add_u64 v[8:9], v[2:3], 0, s[0:1]
	s_mov_b64 s[0:1], 0x1c00
	v_lshl_add_u64 v[10:11], v[2:3], 0, s[0:1]
	s_lshl_b64 s[0:1], s[4:5], 13
	s_add_u32 s2, s2, s0
	s_addc_u32 s3, s3, s1
	s_add_u32 s0, s6, s0
	s_addc_u32 s1, s7, s1
	s_add_u32 s6, s48, s0
	s_addc_u32 s7, s49, s1
	s_mov_b32 s5, 0x20e01000
	global_load_dwordx4 v[100:103], v[2:3], off
	global_load_dwordx4 v[104:107], v[2:3], off offset:1024
	global_load_dwordx4 v[108:111], v[2:3], off offset:2048
	global_load_dwordx4 v[112:115], v[2:3], off offset:3072
	global_load_dwordx4 v[116:119], v[4:5], off
	global_load_dwordx4 v[120:123], v[6:7], off
	global_load_dwordx4 v[124:127], v[8:9], off
	global_load_dwordx4 v[128:131], v[10:11], off
	s_mov_b64 s[98:99], 0x20e00000
	s_mov_b64 s[100:101], 0x1000
	v_lshl_add_u64 v[172:173], s[6:7], 0, v[0:1]
	v_lshl_add_u64 v[172:173], v[172:173], 0, s[98:99]
	v_lshl_add_u64 v[174:175], v[172:173], 0, s[100:101]
	global_load_dwordx4 v[140:143], v[174:175], off
	global_load_dwordx4 v[144:147], v[174:175], off offset:1024
	global_load_dwordx4 v[148:151], v[174:175], off offset:2048
	global_load_dwordx4 v[152:155], v[172:173], off
	global_load_dwordx4 v[156:159], v[172:173], off offset:1024
	global_load_dwordx4 v[160:163], v[172:173], off offset:2048
	global_load_dwordx4 v[164:167], v[172:173], off offset:3072
	global_load_dwordx4 v[168:171], v[174:175], off offset:3072
	s_waitcnt vmcnt(0)
.LBB0_885:
	v_lshl_add_u64 v[56:57], s[2:3], 0, v[0:1]
	s_add_i32 s4, s4, s58
	s_add_u32 s2, s2, s60
	s_addc_u32 s3, s3, s61
	s_add_u32 s6, s6, s60
	s_addc_u32 s7, s7, s61
	s_cmpk_lt_i32 s4, 0x4000
	s_waitcnt vmcnt(8)
	v_mov_b64_e32 v[20:21], v[140:141]
	v_mov_b64_e32 v[22:23], v[142:143]
	v_mov_b64_e32 v[24:25], v[144:145]
	v_mov_b64_e32 v[26:27], v[146:147]
	v_mov_b64_e32 v[28:29], v[148:149]
	v_mov_b64_e32 v[30:31], v[150:151]
	v_mov_b64_e32 v[32:33], v[152:153]
	v_mov_b64_e32 v[34:35], v[154:155]
	v_mov_b64_e32 v[36:37], v[156:157]
	v_mov_b64_e32 v[38:39], v[158:159]
	v_mov_b64_e32 v[40:41], v[160:161]
	v_mov_b64_e32 v[42:43], v[162:163]
	v_mov_b64_e32 v[44:45], v[164:165]
	v_mov_b64_e32 v[46:47], v[166:167]
	v_mov_b64_e32 v[48:49], v[168:169]
	v_mov_b64_e32 v[50:51], v[170:171]
	s_cbranch_scc0 .Lfn_nopf
	v_lshl_add_u64 v[172:173], s[6:7], 0, v[0:1]
	v_lshl_add_u64 v[172:173], v[172:173], 0, s[98:99]
	v_lshl_add_u64 v[174:175], v[172:173], 0, s[100:101]
	global_load_dwordx4 v[140:143], v[174:175], off
	global_load_dwordx4 v[144:147], v[174:175], off offset:1024
	global_load_dwordx4 v[148:151], v[174:175], off offset:2048
	global_load_dwordx4 v[152:155], v[172:173], off
	global_load_dwordx4 v[156:159], v[172:173], off offset:1024
	global_load_dwordx4 v[160:163], v[172:173], off offset:2048
	global_load_dwordx4 v[164:167], v[172:173], off offset:3072
	global_load_dwordx4 v[168:171], v[174:175], off offset:3072
; __global__ void __launch_bounds__(NWAVES * 64, 2) mk_fwd(Args args) {
;     ...
;         for (int m = gw; m < SEQ; m += NGW) {
;             const f32x4* xr = (const f32x4*)(XR + (size_t)m * DMODEL) + lane;
;             f32x4 v[8]; float s = 0.f;
; #pragma unroll
;             for (int j = 0; j < 8; ++j) { v[j] = xr[64 * j]; s += (v[j][0] * v[j][0] + v[j][1] * v[j][1]) + (v[j][2] * v[j][2] + v[j][3] * v[j][3]); }
;             const float rstd = __builtin_amdgcn_rsqf(wave_sum(s) * (1.f / DMODEL) + EPS);
;             f32x4* o = (f32x4*)(out_p + (size_t)m * DMODEL) + lane;
; #pragma unroll
;             for (int j = 0; j < 8; ++j) { const f32x4 g = *((const f32x4*)final_norm_w + lane + 64 * j); o[64 * j] = v[j] * rstd * g; }
.Lfn_nopf:
	v_mul_f32_e32 v81, v21, v21
	v_pk_mul_f32 v[58:59], v[26:27], v[26:27]
	v_pk_mul_f32 v[60:61], v[24:25], v[24:25]
	v_mul_f32_e32 v62, v29, v29
	v_mul_f32_e32 v64, v31, v31
	v_mov_b32_e32 v68, v33
	v_mov_b32_e32 v69, v37
	v_mov_b32_e32 v72, v35
	v_mov_b32_e32 v73, v39
	v_mul_f32_e32 v88, v50, v50
	v_mul_f32_e32 v89, v51, v51
	v_mov_b32_e32 v66, v32
	v_mov_b32_e32 v67, v36
	v_mov_b32_e32 v70, v34
	v_mov_b32_e32 v71, v38
	v_pk_mul_f32 v[74:75], v[42:43], v[42:43]
	v_pk_mul_f32 v[76:77], v[40:41], v[40:41]
	v_pk_mov_b32 v[82:83], v[60:61], v[58:59] op_sel:[1,0]
	v_mov_b32_e32 v61, v59
	v_pk_fma_f32 v[58:59], v[28:29], v[28:29], v[62:63] op_sel_hi:[1,1,0]
	v_pk_fma_f32 v[62:63], v[30:31], v[30:31], v[64:65] op_sel_hi:[1,1,0]
	v_pk_mul_f32 v[64:65], v[68:69], v[68:69]
	v_pk_mul_f32 v[68:69], v[72:73], v[72:73]
	v_pk_mov_b32 v[72:73], v[76:77], v[74:75] op_sel:[1,0]
	v_mov_b32_e32 v77, v75
	v_mov_b32_e32 v59, v88
	v_mov_b32_e32 v63, v89
	v_pk_fma_f32 v[64:65], v[66:67], v[66:67], v[64:65]
	v_pk_fma_f32 v[66:67], v[70:71], v[70:71], v[68:69]
	v_mul_f32_e32 v78, v45, v45
	v_mul_f32_e32 v80, v47, v47
	v_pk_add_f32 v[68:69], v[72:73], v[76:77]
	v_pk_add_f32 v[58:59], v[58:59], v[62:63]
	v_pk_add_f32 v[62:63], v[64:65], v[66:67]
	v_mul_f32_e32 v19, v20, v20
	v_mul_f32_e32 v84, v22, v22
	v_mul_f32_e32 v85, v23, v23
	v_pk_fma_f32 v[74:75], v[44:45], v[44:45], v[78:79] op_sel_hi:[1,1,0]
	v_pk_fma_f32 v[78:79], v[46:47], v[46:47], v[80:81] op_sel_hi:[1,1,0]
	v_pk_add_f32 v[64:65], v[68:69], v[68:69] op_sel:[0,1] op_sel_hi:[1,0]
	v_pk_add_f32 v[62:63], v[62:63], v[62:63] op_sel:[0,1] op_sel_hi:[1,0]
	v_mov_b32_e32 v75, v84
	v_mov_b32_e32 v79, v85
	v_mov_b32_e32 v65, v81
	v_mov_b32_e32 v63, v19
	v_pk_add_f32 v[66:67], v[74:75], v[78:79]
	v_pk_add_f32 v[62:63], v[62:63], v[64:65]
	v_pk_add_f32 v[60:61], v[82:83], v[60:61]
	v_pk_add_f32 v[62:63], v[62:63], v[66:67]
	v_mul_f32_e32 v86, v48, v48
	v_mul_f32_e32 v87, v49, v49
	v_pk_add_f32 v[60:61], v[60:61], v[60:61] op_sel:[0,1] op_sel_hi:[1,0]
	v_pk_add_f32 v[62:63], v[62:63], v[62:63] op_sel:[0,1] op_sel_hi:[1,0]
	v_mov_b32_e32 v61, v87
	v_mov_b32_e32 v63, v86
	v_pk_add_f32 v[60:61], v[62:63], v[60:61]
	s_nop 0
	v_pk_add_f32 v[58:59], v[60:61], v[58:59]
	s_nop 0
	v_add_f32_e32 v19, v58, v59
	ds_bpermute_b32 v58, v12, v19
	s_waitcnt lgkmcnt(0)
	v_add_f32_e32 v19, v19, v58
	ds_bpermute_b32 v58, v13, v19
	s_waitcnt lgkmcnt(0)
	v_add_f32_e32 v19, v19, v58
	ds_bpermute_b32 v58, v14, v19
	s_waitcnt lgkmcnt(0)
	v_add_f32_e32 v19, v19, v58
	ds_bpermute_b32 v58, v15, v19
	s_waitcnt lgkmcnt(0)
	v_add_f32_e32 v19, v19, v58
	ds_bpermute_b32 v58, v16, v19
	s_waitcnt lgkmcnt(0)
	v_add_f32_e32 v19, v19, v58
	ds_bpermute_b32 v58, v17, v19
	s_waitcnt lgkmcnt(0)
	v_add_f32_e32 v19, v19, v58
	v_fmamk_f32 v19, v19, 0x3a000000, v18
	v_rsq_f32_e32 v58, v19
	s_nop 0
	v_pk_mul_f32 v[32:33], v[58:59], v[32:33] op_sel_hi:[0,1]
	v_pk_mul_f32 v[34:35], v[58:59], v[34:35] op_sel_hi:[0,1]
	v_pk_mul_f32 v[34:35], v[102:103], v[34:35]
	v_pk_mul_f32 v[32:33], v[100:101], v[32:33]
	global_store_dwordx4 v[56:57], v[32:35], off
	v_pk_mul_f32 v[38:39], v[58:59], v[38:39] op_sel_hi:[0,1]
	v_pk_mul_f32 v[36:37], v[58:59], v[36:37] op_sel_hi:[0,1]
	v_pk_mul_f32 v[22:23], v[58:59], v[22:23] op_sel_hi:[0,1]
	v_pk_mul_f32 v[20:21], v[58:59], v[20:21] op_sel_hi:[0,1]
	v_pk_mul_f32 v[26:27], v[58:59], v[26:27] op_sel_hi:[0,1]
	v_pk_mul_f32 v[24:25], v[58:59], v[24:25] op_sel_hi:[0,1]
	v_pk_mul_f32 v[32:33], v[104:105], v[36:37]
	v_pk_mul_f32 v[34:35], v[106:107], v[38:39]
	global_store_dwordx4 v[56:57], v[32:35], off offset:1024
	v_pk_mul_f32 v[36:37], v[58:59], v[42:43] op_sel_hi:[0,1]
	v_pk_mul_f32 v[38:39], v[58:59], v[40:41] op_sel_hi:[0,1]
	v_pk_mul_f32 v[32:33], v[108:109], v[38:39]
	v_pk_mul_f32 v[34:35], v[110:111], v[36:37]
	global_store_dwordx4 v[56:57], v[32:35], off offset:2048
	v_pk_mul_f32 v[36:37], v[58:59], v[46:47] op_sel_hi:[0,1]
	v_pk_mul_f32 v[38:39], v[58:59], v[44:45] op_sel_hi:[0,1]
	v_pk_mul_f32 v[32:33], v[112:113], v[38:39]
	v_pk_mul_f32 v[34:35], v[114:115], v[36:37]
	global_store_dwordx4 v[56:57], v[32:35], off offset:3072
	v_add_co_u32_e32 v36, vcc, s8, v56
	v_pk_mul_f32 v[20:21], v[116:117], v[20:21]
	v_addc_co_u32_e32 v37, vcc, 0, v57, vcc
	v_pk_mul_f32 v[22:23], v[118:119], v[22:23]
	global_store_dwordx4 v[36:37], v[20:23], off
	s_nop 1
	v_pk_mul_f32 v[20:21], v[120:121], v[24:25]
	v_pk_mul_f32 v[22:23], v[122:123], v[26:27]
	global_store_dwordx4 v[36:37], v[20:23], off offset:1024
	v_pk_mul_f32 v[24:25], v[58:59], v[30:31] op_sel_hi:[0,1]
	v_pk_mul_f32 v[26:27], v[58:59], v[28:29] op_sel_hi:[0,1]
	v_pk_mul_f32 v[20:21], v[124:125], v[26:27]
	v_pk_mul_f32 v[22:23], v[126:127], v[24:25]
	global_store_dwordx4 v[36:37], v[20:23], off offset:2048
	v_pk_mul_f32 v[24:25], v[58:59], v[50:51] op_sel_hi:[0,1]
	v_pk_mul_f32 v[26:27], v[58:59], v[48:49] op_sel_hi:[0,1]
	v_pk_mul_f32 v[20:21], v[128:129], v[26:27]
	v_pk_mul_f32 v[22:23], v[130:131], v[24:25]
	global_store_dwordx4 v[36:37], v[20:23], off offset:3072
	s_cbranch_scc1 .LBB0_885
